# MoBA unit header: Q-tile loads issued before the kbar loads (one round trip less per unit)
# baseline (speedup 1.0000x reference)
; #define LAS __attribute__((address_space(3)))
;     ...
;     for (int i = tid; i < 256 * 64; i += NTHREADS) oacc[i] = 0.f;
;     if (tid < 256) lsl[tid] = 0.f;
;     if (tid < 32) cnt[tid] = 0;
;     for (int i = tid; i < blk * 64; i += NTHREADS) kb[i] = kbarg[((long)bh * 32) * 64 + i];
;     const int qt = tid >> 1, qh = tid & 1;
;     u32x4 qw[4];
;     {
;       const u32x4* qp = (const u32x4*)(Mq + qbase + (long)qt * 64 + qh * 32);
; #pragma unroll
;       for (int i = 0; i < 4; ++i) { qw[i] = qp[i]; *(LAS u32x4*)(Qs + qt * MO_QS + qh * 64 + i * 16) = qw[i]; }
.LBB0_554:
	s_or_b64 exec, exec, s[16:17]
	s_and_saveexec_b64 s[16:17], s[10:11]
	ds_write_b32 v203, v187
	s_or_b64 exec, exec, s[16:17]
	s_and_saveexec_b64 s[16:17], s[6:7]
	ds_write_b32 v204, v187
	s_or_b64 exec, exec, s[16:17]
	s_ashr_i32 s15, s14, 31
	s_lshl_b32 s19, s18, 6
	s_lshl_b64 s[50:51], s[14:15], 13
	s_lshl_b32 s98, s18, 8
	s_ashr_i32 s99, s98, 31
	s_add_u32 s98, s50, s98
	s_addc_u32 s99, s51, s99
	s_lshl_b64 s[98:99], s[98:99], 7
	v_lshl_add_u64 v[198:199], v[190:191], 0, s[98:99]
	global_load_dwordx4 v[140:143], v[198:199], off
	global_load_dwordx4 v[144:147], v[198:199], off offset:16
	global_load_dwordx4 v[148:151], v[198:199], off offset:32
	global_load_dwordx4 v[152:155], v[198:199], off offset:48
	v_cmp_gt_i32_e32 vcc, s19, v184
	s_and_saveexec_b64 s[16:17], vcc
	s_cbranch_execz .LBB0_573
	v_max_i32_e32 v1, s19, v185
	v_add_u32_e32 v3, v1, v224
	v_cmp_lt_u32_e32 vcc, s73, v3
	s_mov_b64 s[52:53], -1
	v_mov_b32_e32 v2, v184
	v_mov_b32_e32 v1, v195
	s_and_saveexec_b64 s[22:23], vcc
	s_cbranch_execz .LBB0_570
	v_lshrrev_b32_e32 v1, 9, v3
	v_add_u32_e32 v2, -1, v1
	s_add_u32 s52, s58, s50
	v_lshrrev_b32_e32 v3, 1, v2
	s_addc_u32 s53, s60, s51
	v_add_u32_e32 v4, 1, v3
	v_cmp_lt_u32_e32 vcc, 13, v2
	v_mov_b32_e32 v7, 0
	v_mov_b64_e32 v[2:3], v[184:185]
	s_and_saveexec_b64 s[54:55], vcc
	s_cbranch_execz .LBB0_564
	v_and_b32_e32 v5, -8, v4
	s_mov_b32 s21, 0
	s_mov_b64 s[56:57], 0
	v_mov_b32_e32 v6, v229
	v_mov_b64_e32 v[2:3], v[184:185]

; #define LAS __attribute__((address_space(3)))
;     ...
;       for (int i = 0; i < 4; ++i) { qw[i] = qp[i]; *(LAS u32x4*)(Qs + qt * MO_QS + qh * 64 + i * 16) = qw[i]; }
;     }
;     __syncthreads();
;     if (blk > 0) {
;       float q[32];
; #pragma unroll
;       for (int i = 0; i < 4; ++i) { const u32x4 w4 = qw[i]; q[8 * i] = __uint_as_float(w4.x << 16); q[8 * i + 1] = __uint_as_float(w4.x & 0xffff0000u); q[8 * i + 2] = __uint_as_float(w4.y << 16); q[8 * i + 3] = __uint_as_float(w4.y & 0xffff0000u);
;         q[8 * i + 4] = __uint_as_float(w4.z << 16); q[8 * i + 5] = __uint_as_float(w4.z & 0xffff0000u); q[8 * i + 6] = __uint_as_float(w4.w << 16); q[8 * i + 7] = __uint_as_float(w4.w & 0xffff0000u); }
;       float v0 = -3e38f, v1 = -3e38f, v2 = -3e38f; int i0 = -1, i1 = -1, i2 = -1;
.LBB0_573:
	s_or_b64 exec, exec, s[16:17]
	s_cmp_gt_i32 s18, 0
	s_waitcnt vmcnt(0)
	ds_write_b128 v186, v[140:143]
	ds_write_b128 v186, v[144:147] offset:16
	ds_write_b128 v186, v[148:151] offset:32
	ds_write_b128 v186, v[152:155] offset:48
	s_waitcnt lgkmcnt(0)
	s_barrier
	s_cbranch_scc0 .LBB0_589
	v_lshlrev_b32_e32 v100, 16, v140
	v_and_b32_e32 v101, 0xffff0000, v140
	v_lshlrev_b32_e32 v102, 16, v141
	v_and_b32_e32 v103, 0xffff0000, v141
	v_lshlrev_b32_e32 v104, 16, v142
	v_and_b32_e32 v105, 0xffff0000, v142
	v_lshlrev_b32_e32 v106, 16, v143
	v_and_b32_e32 v107, 0xffff0000, v143
	v_lshlrev_b32_e32 v108, 16, v144
	v_and_b32_e32 v109, 0xffff0000, v144
	v_lshlrev_b32_e32 v110, 16, v145
	v_and_b32_e32 v111, 0xffff0000, v145
	v_lshlrev_b32_e32 v112, 16, v146
	v_and_b32_e32 v113, 0xffff0000, v146
	v_lshlrev_b32_e32 v114, 16, v147
	v_and_b32_e32 v115, 0xffff0000, v147
	v_lshlrev_b32_e32 v116, 16, v148
	v_and_b32_e32 v117, 0xffff0000, v148
	v_lshlrev_b32_e32 v118, 16, v149
	v_and_b32_e32 v119, 0xffff0000, v149
	v_lshlrev_b32_e32 v120, 16, v150
	v_and_b32_e32 v121, 0xffff0000, v150
	v_lshlrev_b32_e32 v122, 16, v151
	v_and_b32_e32 v123, 0xffff0000, v151
	v_lshlrev_b32_e32 v124, 16, v152
	v_and_b32_e32 v125, 0xffff0000, v152
	v_lshlrev_b32_e32 v126, 16, v153
	v_and_b32_e32 v127, 0xffff0000, v153
	v_lshlrev_b32_e32 v128, 16, v154
	v_and_b32_e32 v129, 0xffff0000, v154
	v_lshlrev_b32_e32 v130, 16, v155
	v_and_b32_e32 v131, 0xffff0000, v155
	v_mov_b32_e32 v132, 0xff61b1e6
	v_mov_b32_e32 v133, 0xff61b1e6
	v_mov_b32_e32 v134, 0xff61b1e6
	v_mov_b32_e32 v135, -1
	v_mov_b32_e32 v136, -1
	v_mov_b32_e32 v137, -1
	s_mov_b32 s19, 0
	v_mov_b32_e32 v3, v231
	ds_read_b128 v[36:39], v3 offset:0
	ds_read_b128 v[40:43], v3 offset:16
	ds_read_b128 v[44:47], v3 offset:32
	ds_read_b128 v[48:51], v3 offset:48
	ds_read_b128 v[52:55], v3 offset:64
	ds_read_b128 v[56:59], v3 offset:80
	ds_read_b128 v[60:63], v3 offset:96
	ds_read_b128 v[64:67], v3 offset:112
